# DeltaNet scan output rows stored write-through (sc1) and the scan-direction publish no longer does an L2 writeback (documented write-through hand-off)
# baseline (speedup 1.0000x reference)
.LBB0_131:
	v_cmp_eq_u32_e32 vcc, 0, v225
	s_and_saveexec_b64 s[0:1], vcc
	s_cbranch_execz .LBB0_134
	s_mov_b64 s[2:3], exec
	v_mbcnt_lo_u32_b32 v0, s2, 0
	s_waitcnt vmcnt(0) lgkmcnt(0)
	s_waitcnt vmcnt(0)
	v_mbcnt_hi_u32_b32 v0, s3, v0
	v_cmp_eq_u32_e32 vcc, 0, v0
	s_and_b64 s[4:5], exec, vcc
	s_mov_b64 exec, s[4:5]
	s_cbranch_execz .LBB0_134
	v_readlane_b32 s4, v250, 5
	v_readlane_b32 s5, v250, 6
	s_lshl_b32 s4, s4, 6
	s_ashr_i32 s5, s4, 31
	s_lshl_b64 s[4:5], s[4:5], 2
	v_readlane_b32 s6, v251, 8
	s_add_u32 s4, s6, s4
	v_readlane_b32 s6, v251, 9
	s_addc_u32 s5, s6, s5
	s_bcnt1_i32_b64 s2, s[2:3]
	v_mov_b32_e32 v0, s2
	global_atomic_add v65, v0, s[4:5]
